# GEMM next-unit index math: shift/mask fast path when the row-tile group size is 8 (generic division kept as fallback)
# baseline (speedup 1.0000x reference)
;     DI bool next(int i, Unit& u) const {
;         const long L = (long)i * G + c; if (L >= nwg) return false;
;         int wgid = (int)L; { const int q = nwg / NXCD, r = nwg % NXCD, xcd = wgid % NXCD, off = wgid / NXCD; wgid = (xcd < r ? xcd * (q + 1) : r * (q + 1) + (xcd - r) * q) + off; }
;         const int nig = WGM * nN, gid = wgid / nig, fm = gid * WGM, gsz = (nM - fm) < WGM ? (nM - fm) : WGM;
;         u.pm = fm + ((wgid % nig) % gsz); u.pn = (wgid % nig) / gsz; return true;
;     }
.LBB0_234:
	s_add_i32 s2, s2, 1
	s_mul_i32 s11, s2, s35
	s_mul_hi_u32 s12, s2, s22
	s_add_i32 s11, s12, s11
	s_mul_i32 s12, s2, s22
	s_add_u32 s12, s12, s23
	s_addc_u32 s13, s11, s4
	v_mov_b64_e32 v[2:3], s[6:7]
	v_cmp_ge_i64_e64 s[40:41], s[12:13], v[2:3]
	v_cmp_lt_i64_e64 s[42:43], s[12:13], v[2:3]
	s_and_b64 vcc, exec, s[40:41]
	s_cbranch_vccnz .LBB0_236
	s_ashr_i32 s11, s12, 31
	s_lshr_b32 s11, s11, 29
	s_add_i32 s11, s12, s11
	s_ashr_i32 s13, s11, 3
	s_and_b32 s11, s11, -8
	s_sub_i32 s11, s12, s11
	s_lshr_b32 s12, s11, 31
	s_or_b32 s12, s5, s12
	s_mul_i32 s11, s12, s11
	s_add_i32 s11, s11, s13
	s_abs_i32 s13, s11
	s_mul_hi_u32 s14, s13, s69
	s_mul_i32 s15, s14, s87
	s_sub_i32 s13, s13, s15
	s_ashr_i32 s12, s11, 31
	s_add_i32 s15, s14, 1
	s_sub_i32 s20, s13, s87
	s_cmp_ge_u32 s13, s87
	s_cselect_b32 s14, s15, s14
	s_cselect_b32 s13, s20, s13
	s_add_i32 s15, s14, 1
	s_cmp_ge_u32 s13, s87
	s_cselect_b32 s13, s15, s14
	s_xor_b32 s13, s13, s12
	s_sub_i32 s12, s13, s12
	s_lshl_b32 s13, s12, 3
	s_sub_i32 s14, s34, s13
	s_min_i32 s14, s14, 8
	s_cmp_lg_u32 s14, 8
	s_cbranch_scc1 .Lunit_generic
	s_mul_i32 s12, s12, s87
	s_sub_i32 s11, s11, s12
	s_lshr_b32 s31, s11, 3
	s_and_b32 s11, s11, 7
	s_add_i32 s71, s11, s13
	s_branch .LBB0_236
.Lunit_generic:
	s_abs_i32 s15, s14
	v_cvt_f32_u32_e32 v0, s15
	s_sub_i32 s21, 0, s15
	s_mul_i32 s12, s12, s87
	s_sub_i32 s11, s11, s12
	v_rcp_iflag_f32_e32 v0, v0
	s_abs_i32 s20, s11
	s_xor_b32 s12, s11, s14
	s_ashr_i32 s12, s12, 31
	v_mul_f32_e32 v0, 0x4f7ffffe, v0
	v_cvt_u32_f32_e32 v0, v0
	s_nop 0
	v_readfirstlane_b32 s31, v0
	s_mul_i32 s21, s21, s31
	s_mul_hi_u32 s21, s31, s21
	s_add_i32 s31, s31, s21
	s_mul_hi_u32 s21, s20, s31
	s_mul_i32 s31, s21, s15
	s_sub_i32 s20, s20, s31
	s_add_i32 s31, s21, 1
	s_sub_i32 s37, s20, s15
	s_cmp_ge_u32 s20, s15
	s_cselect_b32 s21, s31, s21
	s_cselect_b32 s20, s37, s20
	s_add_i32 s31, s21, 1
	s_cmp_ge_u32 s20, s15
	s_cselect_b32 s15, s31, s21
	s_xor_b32 s15, s15, s12
	s_sub_i32 s31, s15, s12
	s_mul_i32 s12, s31, s14
	s_sub_i32 s11, s11, s12
	s_add_i32 s71, s11, s13
